# v019-early-L1-invalidate-at-barrier-arrival
# speedup vs baseline: 1.0176x; 1.0111x over previous
; __device__ __forceinline__ unsigned xb_ld(unsigned* p)              { return __hip_atomic_load(p, __ATOMIC_RELAXED, __HIP_MEMORY_SCOPE_AGENT); }
; __device__ __forceinline__ unsigned xb_add(unsigned* p, unsigned v) { return __hip_atomic_fetch_add(p, v, __ATOMIC_RELAXED, __HIP_MEMORY_SCOPE_AGENT); }
; #define XB_SPIN(cond, bar) do { unsigned _sp = 0; while (cond) { __builtin_amdgcn_s_sleep(1); \
;     if ((++_sp & 255u) == 0u) { if (xb_ld(&(bar)[XB_TMO])) break; if (_sp > XB_SPIN_CAP) { atomicAdd(&(bar)[XB_TMO], 1u); break; } } } } while (0)
; __device__ __forceinline__ void xcd_barrier(const XcdBarrier& b) {
;     ...
;         const unsigned old = xb_add(&bar[XB_XSUB(b.x)], 1u);
;         const unsigned gen = old / nloc;
;         if (old + 1u == (gen + 1u) * nloc) {
;             __builtin_amdgcn_fence(__ATOMIC_RELEASE, "agent");
;             asm volatile("s_waitcnt vmcnt(0)" ::: "memory");
;             const unsigned og = xb_add(&bar[XB_TOP], 1u);
;             const unsigned tg = og / nx;
;             if (og + 1u == (tg + 1u) * nx) xb_add(&bar[XB_TOPGEN], 1u);
;             else XB_SPIN(xb_ld(&bar[XB_TOPGEN]) == tg, bar);
;             __builtin_amdgcn_fence(__ATOMIC_ACQUIRE, "agent");
;             xb_add(&bar[XB_XGEN(b.x)], 1u);
;             asm volatile("s_waitcnt vmcnt(0)" ::: "memory");
;         } else {
;             XB_SPIN(xb_ld(&bar[XB_XGEN(b.x)]) == gen, bar);
;             __builtin_amdgcn_fence(__ATOMIC_ACQUIRE, "agent");
;             asm volatile("s_waitcnt vmcnt(0)" ::: "memory");
.LBB0_165:
	s_or_b64 exec, exec, s[22:23]
	v_cvt_f32_u32_e32 v4, v2
	s_waitcnt vmcnt(0)
	v_readfirstlane_b32 s2, v3
	v_sub_u32_e32 v3, 0, v2
	v_rcp_iflag_f32_e32 v4, v4
	v_add_u32_e32 v5, s2, v1
	v_mul_f32_e32 v4, 0x4f7ffffe, v4
	v_cvt_u32_f32_e32 v4, v4
	v_mul_lo_u32 v1, v3, v4
	v_mul_hi_u32 v1, v4, v1
	v_add_u32_e32 v1, v4, v1
	v_mul_hi_u32 v1, v5, v1
	v_mul_lo_u32 v3, v1, v2
	v_sub_u32_e32 v3, v5, v3
	v_add_u32_e32 v4, 1, v1
	v_cmp_ge_u32_e32 vcc, v3, v2
	s_nop 1
	v_cndmask_b32_e32 v1, v1, v4, vcc
	v_sub_u32_e32 v4, v3, v2
	v_cndmask_b32_e32 v3, v3, v4, vcc
	v_add_u32_e32 v4, 1, v1
	v_cmp_ge_u32_e32 vcc, v3, v2
	v_add_u32_e32 v3, 1, v5
	s_nop 0
	v_cndmask_b32_e32 v1, v1, v4, vcc
	v_mul_lo_u32 v4, v2, v1
	v_add_u32_e32 v2, v4, v2
	v_cmp_ne_u32_e32 vcc, v3, v2
	s_and_saveexec_b64 s[10:11], vcc
	s_xor_b64 s[20:21], exec, s[10:11]
	s_cbranch_execz .LBB0_179
	buffer_inv sc1
	s_waitcnt lgkmcnt(0)
	v_mov_b32_e32 v0, 0x2000
	global_load_dword v0, v0, s[6:7] offset:1024 sc1
	s_add_u32 s24, s6, 0x2400
	s_addc_u32 s25, s7, 0
	s_waitcnt vmcnt(0)
	v_cmp_eq_u32_e32 vcc, v0, v1
	s_and_saveexec_b64 s[22:23], vcc
	s_cbranch_execz .LBB0_178
	s_mov_b32 s2, 1
	s_mov_b64 s[26:27], 0
	v_mov_b32_e32 v0, 0
	s_branch .LBB0_169

; __device__ __forceinline__ unsigned xb_ld(unsigned* p)              { return __hip_atomic_load(p, __ATOMIC_RELAXED, __HIP_MEMORY_SCOPE_AGENT); }
; __device__ __forceinline__ unsigned xb_add(unsigned* p, unsigned v) { return __hip_atomic_fetch_add(p, v, __ATOMIC_RELAXED, __HIP_MEMORY_SCOPE_AGENT); }
; #define XB_SPIN(cond, bar) do { unsigned _sp = 0; while (cond) { __builtin_amdgcn_s_sleep(1); \
;     if ((++_sp & 255u) == 0u) { if (xb_ld(&(bar)[XB_TMO])) break; if (_sp > XB_SPIN_CAP) { atomicAdd(&(bar)[XB_TMO], 1u); break; } } } } while (0)
; __device__ __forceinline__ void xcd_barrier(const XcdBarrier& b) {
;     ...
;         if (old + 1u == (gen + 1u) * nloc) {
;             __builtin_amdgcn_fence(__ATOMIC_RELEASE, "agent");
;             asm volatile("s_waitcnt vmcnt(0)" ::: "memory");
;             const unsigned og = xb_add(&bar[XB_TOP], 1u);
;             const unsigned tg = og / nx;
;             if (og + 1u == (tg + 1u) * nx) xb_add(&bar[XB_TOPGEN], 1u);
;             else XB_SPIN(xb_ld(&bar[XB_TOPGEN]) == tg, bar);
;             __builtin_amdgcn_fence(__ATOMIC_ACQUIRE, "agent");
;             xb_add(&bar[XB_XGEN(b.x)], 1u);
;             asm volatile("s_waitcnt vmcnt(0)" ::: "memory");
;         } else {
;             XB_SPIN(xb_ld(&bar[XB_XGEN(b.x)]) == gen, bar);
;             __builtin_amdgcn_fence(__ATOMIC_ACQUIRE, "agent");
;             asm volatile("s_waitcnt vmcnt(0)" ::: "memory");
.LBB0_178:
	s_or_b64 exec, exec, s[22:23]
	s_waitcnt vmcnt(0)
	s_waitcnt vmcnt(0)
.LBB0_179:
	s_andn2_saveexec_b64 s[10:11], s[20:21]
	s_cbranch_execz .LBB0_199
	s_mov_b64 s[20:21], exec
	buffer_wbl2 sc1
	buffer_inv sc1
	s_waitcnt lgkmcnt(0)
	s_waitcnt vmcnt(0)
	v_mbcnt_lo_u32_b32 v1, s20, 0
	v_mbcnt_hi_u32_b32 v1, s21, v1
	v_cmp_eq_u32_e32 vcc, 0, v1
	s_and_saveexec_b64 s[22:23], vcc
	s_cbranch_execz .LBB0_182
	s_bcnt1_i32_b64 s2, s[20:21]
	v_mov_b32_e32 v2, 0x3000
	v_mov_b32_e32 v3, s2
	global_atomic_add v2, v2, v3, s[90:91] offset:1024 sc0

; __device__ __forceinline__ unsigned xb_ld(unsigned* p)              { return __hip_atomic_load(p, __ATOMIC_RELAXED, __HIP_MEMORY_SCOPE_AGENT); }
; __device__ __forceinline__ unsigned xb_add(unsigned* p, unsigned v) { return __hip_atomic_fetch_add(p, v, __ATOMIC_RELAXED, __HIP_MEMORY_SCOPE_AGENT); }
; #define XB_SPIN(cond, bar) do { unsigned _sp = 0; while (cond) { __builtin_amdgcn_s_sleep(1); \
;     if ((++_sp & 255u) == 0u) { if (xb_ld(&(bar)[XB_TMO])) break; if (_sp > XB_SPIN_CAP) { atomicAdd(&(bar)[XB_TMO], 1u); break; } } } } while (0)
; __device__ __forceinline__ void xcd_barrier(const XcdBarrier& b) {
;     ...
;             else XB_SPIN(xb_ld(&bar[XB_TOPGEN]) == tg, bar);
;             __builtin_amdgcn_fence(__ATOMIC_ACQUIRE, "agent");
;             xb_add(&bar[XB_XGEN(b.x)], 1u);
.LBB0_196:
	s_or_b64 exec, exec, s[20:21]
	s_mov_b64 s[20:21], exec
	v_mbcnt_lo_u32_b32 v0, s20, 0
	v_mbcnt_hi_u32_b32 v0, s21, v0
	v_cmp_eq_u32_e32 vcc, 0, v0
	s_waitcnt vmcnt(0)
	s_and_saveexec_b64 s[22:23], vcc
	s_cbranch_execz .LBB0_198
	s_bcnt1_i32_b64 s2, s[20:21]
	v_mov_b32_e32 v0, 0x2000
	v_mov_b32_e32 v1, s2
	global_atomic_add v0, v1, s[6:7] offset:1024

; __device__ __forceinline__ unsigned xb_ld(unsigned* p)              { return __hip_atomic_load(p, __ATOMIC_RELAXED, __HIP_MEMORY_SCOPE_AGENT); }
; __device__ __forceinline__ unsigned xb_add(unsigned* p, unsigned v) { return __hip_atomic_fetch_add(p, v, __ATOMIC_RELAXED, __HIP_MEMORY_SCOPE_AGENT); }
; #define XB_SPIN(cond, bar) do { unsigned _sp = 0; while (cond) { __builtin_amdgcn_s_sleep(1); \
;     if ((++_sp & 255u) == 0u) { if (xb_ld(&(bar)[XB_TMO])) break; if (_sp > XB_SPIN_CAP) { atomicAdd(&(bar)[XB_TMO], 1u); break; } } } } while (0)
; __device__ __forceinline__ void xcd_barrier(const XcdBarrier& b) {
;     ...
;         const unsigned old = xb_add(&bar[XB_XSUB(b.x)], 1u);
;         const unsigned gen = old / nloc;
;         if (old + 1u == (gen + 1u) * nloc) {
;             __builtin_amdgcn_fence(__ATOMIC_RELEASE, "agent");
;             asm volatile("s_waitcnt vmcnt(0)" ::: "memory");
;             const unsigned og = xb_add(&bar[XB_TOP], 1u);
;             const unsigned tg = og / nx;
;             if (og + 1u == (tg + 1u) * nx) xb_add(&bar[XB_TOPGEN], 1u);
;             else XB_SPIN(xb_ld(&bar[XB_TOPGEN]) == tg, bar);
;             __builtin_amdgcn_fence(__ATOMIC_ACQUIRE, "agent");
;             xb_add(&bar[XB_XGEN(b.x)], 1u);
;             asm volatile("s_waitcnt vmcnt(0)" ::: "memory");
;         } else {
;             XB_SPIN(xb_ld(&bar[XB_XGEN(b.x)]) == gen, bar);
;             __builtin_amdgcn_fence(__ATOMIC_ACQUIRE, "agent");
;             asm volatile("s_waitcnt vmcnt(0)" ::: "memory");
.LBB0_303:
	s_or_b64 exec, exec, s[22:23]
	v_cvt_f32_u32_e32 v4, v2
	s_waitcnt vmcnt(0)
	v_readfirstlane_b32 s2, v3
	v_sub_u32_e32 v3, 0, v2
	v_rcp_iflag_f32_e32 v4, v4
	v_add_u32_e32 v5, s2, v1
	v_mul_f32_e32 v4, 0x4f7ffffe, v4
	v_cvt_u32_f32_e32 v4, v4
	v_mul_lo_u32 v1, v3, v4
	v_mul_hi_u32 v1, v4, v1
	v_add_u32_e32 v1, v4, v1
	v_mul_hi_u32 v1, v5, v1
	v_mul_lo_u32 v3, v1, v2
	v_sub_u32_e32 v3, v5, v3
	v_add_u32_e32 v4, 1, v1
	v_cmp_ge_u32_e32 vcc, v3, v2
	s_nop 1
	v_cndmask_b32_e32 v1, v1, v4, vcc
	v_sub_u32_e32 v4, v3, v2
	v_cndmask_b32_e32 v3, v3, v4, vcc
	v_add_u32_e32 v4, 1, v1
	v_cmp_ge_u32_e32 vcc, v3, v2
	v_add_u32_e32 v3, 1, v5
	s_nop 0
	v_cndmask_b32_e32 v1, v1, v4, vcc
	v_mul_lo_u32 v4, v2, v1
	v_add_u32_e32 v2, v4, v2
	v_cmp_ne_u32_e32 vcc, v3, v2
	s_and_saveexec_b64 s[12:13], vcc
	s_xor_b64 s[20:21], exec, s[12:13]
	s_cbranch_execz .LBB0_317
	buffer_inv sc1
	s_waitcnt lgkmcnt(0)
	v_mov_b32_e32 v0, 0x2000
	global_load_dword v0, v0, s[18:19] offset:1024 sc1
	s_add_u32 s24, s18, 0x2400
	s_addc_u32 s25, s19, 0
	s_waitcnt vmcnt(0)
	v_cmp_eq_u32_e32 vcc, v0, v1
	s_and_saveexec_b64 s[22:23], vcc
	s_cbranch_execz .LBB0_316
	s_mov_b32 s2, 1
	s_mov_b64 s[26:27], 0
	v_mov_b32_e32 v0, 0
	s_branch .LBB0_307

; __device__ __forceinline__ unsigned xb_add(unsigned* p, unsigned v) { return __hip_atomic_fetch_add(p, v, __ATOMIC_RELAXED, __HIP_MEMORY_SCOPE_AGENT); }
; __device__ __forceinline__ void xcd_barrier(const XcdBarrier& b) {
;     ...
;         if (old + 1u == (gen + 1u) * nloc) {
;             __builtin_amdgcn_fence(__ATOMIC_RELEASE, "agent");
;             asm volatile("s_waitcnt vmcnt(0)" ::: "memory");
;             const unsigned og = xb_add(&bar[XB_TOP], 1u);
.LBB0_317:
	s_andn2_saveexec_b64 s[12:13], s[20:21]
	s_cbranch_execz .LBB0_337
	s_mov_b64 s[20:21], exec
	buffer_wbl2 sc1
	buffer_inv sc1
	s_waitcnt lgkmcnt(0)
	s_waitcnt vmcnt(0)
	v_mbcnt_lo_u32_b32 v1, s20, 0
	v_mbcnt_hi_u32_b32 v1, s21, v1
	v_cmp_eq_u32_e32 vcc, 0, v1
	s_and_saveexec_b64 s[22:23], vcc
	s_cbranch_execz .LBB0_320
	s_bcnt1_i32_b64 s2, s[20:21]
	v_mov_b32_e32 v2, 0x3000
	v_mov_b32_e32 v3, s2
	global_atomic_add v2, v2, v3, s[90:91] offset:1024 sc0

; __device__ __forceinline__ unsigned xb_ld(unsigned* p)              { return __hip_atomic_load(p, __ATOMIC_RELAXED, __HIP_MEMORY_SCOPE_AGENT); }
; __device__ __forceinline__ unsigned xb_add(unsigned* p, unsigned v) { return __hip_atomic_fetch_add(p, v, __ATOMIC_RELAXED, __HIP_MEMORY_SCOPE_AGENT); }
; #define XB_SPIN(cond, bar) do { unsigned _sp = 0; while (cond) { __builtin_amdgcn_s_sleep(1); \
;     if ((++_sp & 255u) == 0u) { if (xb_ld(&(bar)[XB_TMO])) break; if (_sp > XB_SPIN_CAP) { atomicAdd(&(bar)[XB_TMO], 1u); break; } } } } while (0)
; __device__ __forceinline__ void xcd_barrier(const XcdBarrier& b) {
;     ...
;             if (og + 1u == (tg + 1u) * nx) xb_add(&bar[XB_TOPGEN], 1u);
;             else XB_SPIN(xb_ld(&bar[XB_TOPGEN]) == tg, bar);
;             __builtin_amdgcn_fence(__ATOMIC_ACQUIRE, "agent");
;             xb_add(&bar[XB_XGEN(b.x)], 1u);
.LBB0_334:
	s_or_b64 exec, exec, s[20:21]
	s_mov_b64 s[20:21], exec
	v_mbcnt_lo_u32_b32 v0, s20, 0
	v_mbcnt_hi_u32_b32 v0, s21, v0
	v_cmp_eq_u32_e32 vcc, 0, v0
	s_waitcnt vmcnt(0)
	s_and_saveexec_b64 s[22:23], vcc
	s_cbranch_execz .LBB0_336
	s_bcnt1_i32_b64 s2, s[20:21]
	v_mov_b32_e32 v0, 0x2000
	v_mov_b32_e32 v1, s2
	global_atomic_add v0, v1, s[18:19] offset:1024

; __device__ __forceinline__ unsigned xb_ld(unsigned* p)              { return __hip_atomic_load(p, __ATOMIC_RELAXED, __HIP_MEMORY_SCOPE_AGENT); }
; __device__ __forceinline__ unsigned xb_add(unsigned* p, unsigned v) { return __hip_atomic_fetch_add(p, v, __ATOMIC_RELAXED, __HIP_MEMORY_SCOPE_AGENT); }
; #define XB_SPIN(cond, bar) do { unsigned _sp = 0; while (cond) { __builtin_amdgcn_s_sleep(1); \
;     if ((++_sp & 255u) == 0u) { if (xb_ld(&(bar)[XB_TMO])) break; if (_sp > XB_SPIN_CAP) { atomicAdd(&(bar)[XB_TMO], 1u); break; } } } } while (0)
; __device__ __forceinline__ void xcd_barrier(const XcdBarrier& b) {
;     ...
;         const unsigned old = xb_add(&bar[XB_XSUB(b.x)], 1u);
;         const unsigned gen = old / nloc;
;         if (old + 1u == (gen + 1u) * nloc) {
;             __builtin_amdgcn_fence(__ATOMIC_RELEASE, "agent");
;             asm volatile("s_waitcnt vmcnt(0)" ::: "memory");
;             const unsigned og = xb_add(&bar[XB_TOP], 1u);
;             const unsigned tg = og / nx;
;             if (og + 1u == (tg + 1u) * nx) xb_add(&bar[XB_TOPGEN], 1u);
;             else XB_SPIN(xb_ld(&bar[XB_TOPGEN]) == tg, bar);
;             __builtin_amdgcn_fence(__ATOMIC_ACQUIRE, "agent");
;             xb_add(&bar[XB_XGEN(b.x)], 1u);
;             asm volatile("s_waitcnt vmcnt(0)" ::: "memory");
;         } else {
;             XB_SPIN(xb_ld(&bar[XB_XGEN(b.x)]) == gen, bar);
;             __builtin_amdgcn_fence(__ATOMIC_ACQUIRE, "agent");
;             asm volatile("s_waitcnt vmcnt(0)" ::: "memory");
.LBB0_471:
	s_or_b64 exec, exec, s[22:23]
	v_cvt_f32_u32_e32 v4, v2
	s_waitcnt vmcnt(0)
	v_readfirstlane_b32 s2, v3
	v_sub_u32_e32 v3, 0, v2
	v_rcp_iflag_f32_e32 v4, v4
	v_add_u32_e32 v5, s2, v1
	v_mul_f32_e32 v4, 0x4f7ffffe, v4
	v_cvt_u32_f32_e32 v4, v4
	v_mul_lo_u32 v1, v3, v4
	v_mul_hi_u32 v1, v4, v1
	v_add_u32_e32 v1, v4, v1
	v_mul_hi_u32 v1, v5, v1
	v_mul_lo_u32 v3, v1, v2
	v_sub_u32_e32 v3, v5, v3
	v_add_u32_e32 v4, 1, v1
	v_cmp_ge_u32_e32 vcc, v3, v2
	s_nop 1
	v_cndmask_b32_e32 v1, v1, v4, vcc
	v_sub_u32_e32 v4, v3, v2
	v_cndmask_b32_e32 v3, v3, v4, vcc
	v_add_u32_e32 v4, 1, v1
	v_cmp_ge_u32_e32 vcc, v3, v2
	v_add_u32_e32 v3, 1, v5
	s_nop 0
	v_cndmask_b32_e32 v1, v1, v4, vcc
	v_mul_lo_u32 v4, v2, v1
	v_add_u32_e32 v2, v4, v2
	v_cmp_ne_u32_e32 vcc, v3, v2
	s_and_saveexec_b64 s[12:13], vcc
	s_xor_b64 s[20:21], exec, s[12:13]
	s_cbranch_execz .LBB0_485
	buffer_inv sc1
	s_waitcnt lgkmcnt(0)
	v_mov_b32_e32 v0, 0x2000
	global_load_dword v0, v0, s[6:7] offset:1024 sc1
	s_add_u32 s24, s6, 0x2400
	s_addc_u32 s25, s7, 0
	s_waitcnt vmcnt(0)
	v_cmp_eq_u32_e32 vcc, v0, v1
	s_and_saveexec_b64 s[22:23], vcc
	s_cbranch_execz .LBB0_484
	s_mov_b32 s2, 1
	s_mov_b64 s[26:27], 0
	v_mov_b32_e32 v0, 0
	s_branch .LBB0_475

; __device__ __forceinline__ unsigned xb_ld(unsigned* p)              { return __hip_atomic_load(p, __ATOMIC_RELAXED, __HIP_MEMORY_SCOPE_AGENT); }
; __device__ __forceinline__ unsigned xb_add(unsigned* p, unsigned v) { return __hip_atomic_fetch_add(p, v, __ATOMIC_RELAXED, __HIP_MEMORY_SCOPE_AGENT); }
; #define XB_SPIN(cond, bar) do { unsigned _sp = 0; while (cond) { __builtin_amdgcn_s_sleep(1); \
;     if ((++_sp & 255u) == 0u) { if (xb_ld(&(bar)[XB_TMO])) break; if (_sp > XB_SPIN_CAP) { atomicAdd(&(bar)[XB_TMO], 1u); break; } } } } while (0)
; __device__ __forceinline__ void xcd_barrier(const XcdBarrier& b) {
;     ...
;         const unsigned old = xb_add(&bar[XB_XSUB(b.x)], 1u);
;         const unsigned gen = old / nloc;
;         if (old + 1u == (gen + 1u) * nloc) {
;             __builtin_amdgcn_fence(__ATOMIC_RELEASE, "agent");
;             asm volatile("s_waitcnt vmcnt(0)" ::: "memory");
;             const unsigned og = xb_add(&bar[XB_TOP], 1u);
;             const unsigned tg = og / nx;
;             if (og + 1u == (tg + 1u) * nx) xb_add(&bar[XB_TOPGEN], 1u);
;             else XB_SPIN(xb_ld(&bar[XB_TOPGEN]) == tg, bar);
;             __builtin_amdgcn_fence(__ATOMIC_ACQUIRE, "agent");
;             xb_add(&bar[XB_XGEN(b.x)], 1u);
;             asm volatile("s_waitcnt vmcnt(0)" ::: "memory");
;         } else {
;             XB_SPIN(xb_ld(&bar[XB_XGEN(b.x)]) == gen, bar);
;             __builtin_amdgcn_fence(__ATOMIC_ACQUIRE, "agent");
;             asm volatile("s_waitcnt vmcnt(0)" ::: "memory");
.LBB0_674:
	s_or_b64 exec, exec, s[20:21]
	v_cvt_f32_u32_e32 v4, v2
	s_waitcnt vmcnt(0)
	v_readfirstlane_b32 s2, v3
	v_sub_u32_e32 v3, 0, v2
	v_rcp_iflag_f32_e32 v4, v4
	v_add_u32_e32 v5, s2, v1
	v_mul_f32_e32 v4, 0x4f7ffffe, v4
	v_cvt_u32_f32_e32 v4, v4
	v_mul_lo_u32 v1, v3, v4
	v_mul_hi_u32 v1, v4, v1
	v_add_u32_e32 v1, v4, v1
	v_mul_hi_u32 v1, v5, v1
	v_mul_lo_u32 v3, v1, v2
	v_sub_u32_e32 v3, v5, v3
	v_add_u32_e32 v4, 1, v1
	v_cmp_ge_u32_e32 vcc, v3, v2
	s_nop 1
	v_cndmask_b32_e32 v1, v1, v4, vcc
	v_sub_u32_e32 v4, v3, v2
	v_cndmask_b32_e32 v3, v3, v4, vcc
	v_add_u32_e32 v4, 1, v1
	v_cmp_ge_u32_e32 vcc, v3, v2
	v_add_u32_e32 v3, 1, v5
	s_nop 0
	v_cndmask_b32_e32 v1, v1, v4, vcc
	v_mul_lo_u32 v4, v2, v1
	v_add_u32_e32 v2, v4, v2
	v_cmp_ne_u32_e32 vcc, v3, v2
	s_and_saveexec_b64 s[12:13], vcc
	s_xor_b64 s[18:19], exec, s[12:13]
	s_cbranch_execz .LBB0_688
	buffer_inv sc1
	s_waitcnt lgkmcnt(0)
	v_mov_b32_e32 v0, 0x2000
	global_load_dword v0, v0, s[16:17] offset:1024 sc1
	s_add_u32 s22, s16, 0x2400
	s_addc_u32 s23, s17, 0
	s_waitcnt vmcnt(0)
	v_cmp_eq_u32_e32 vcc, v0, v1
	s_and_saveexec_b64 s[20:21], vcc
	s_cbranch_execz .LBB0_687
	s_mov_b32 s2, 1
	s_mov_b64 s[24:25], 0
	v_mov_b32_e32 v0, 0
	s_branch .LBB0_678

; __device__ __forceinline__ unsigned xb_ld(unsigned* p)              { return __hip_atomic_load(p, __ATOMIC_RELAXED, __HIP_MEMORY_SCOPE_AGENT); }
; __device__ __forceinline__ unsigned xb_add(unsigned* p, unsigned v) { return __hip_atomic_fetch_add(p, v, __ATOMIC_RELAXED, __HIP_MEMORY_SCOPE_AGENT); }
; #define XB_SPIN(cond, bar) do { unsigned _sp = 0; while (cond) { __builtin_amdgcn_s_sleep(1); \
;     if ((++_sp & 255u) == 0u) { if (xb_ld(&(bar)[XB_TMO])) break; if (_sp > XB_SPIN_CAP) { atomicAdd(&(bar)[XB_TMO], 1u); break; } } } } while (0)
; __device__ __forceinline__ void xcd_barrier(const XcdBarrier& b) {
;     ...
;         if (old + 1u == (gen + 1u) * nloc) {
;             __builtin_amdgcn_fence(__ATOMIC_RELEASE, "agent");
;             asm volatile("s_waitcnt vmcnt(0)" ::: "memory");
;             const unsigned og = xb_add(&bar[XB_TOP], 1u);
;             const unsigned tg = og / nx;
;             if (og + 1u == (tg + 1u) * nx) xb_add(&bar[XB_TOPGEN], 1u);
;             else XB_SPIN(xb_ld(&bar[XB_TOPGEN]) == tg, bar);
;             __builtin_amdgcn_fence(__ATOMIC_ACQUIRE, "agent");
;             xb_add(&bar[XB_XGEN(b.x)], 1u);
;             asm volatile("s_waitcnt vmcnt(0)" ::: "memory");
;         } else {
;             XB_SPIN(xb_ld(&bar[XB_XGEN(b.x)]) == gen, bar);
;             __builtin_amdgcn_fence(__ATOMIC_ACQUIRE, "agent");
;             asm volatile("s_waitcnt vmcnt(0)" ::: "memory");
.LBB0_687:
	s_or_b64 exec, exec, s[20:21]
	s_waitcnt vmcnt(0)
	s_waitcnt vmcnt(0)
.LBB0_688:
	s_andn2_saveexec_b64 s[12:13], s[18:19]
	s_cbranch_execz .LBB0_708
	s_mov_b64 s[18:19], exec
	buffer_wbl2 sc1
	buffer_inv sc1
	s_waitcnt lgkmcnt(0)
	s_waitcnt vmcnt(0)
	v_mbcnt_lo_u32_b32 v1, s18, 0
	v_mbcnt_hi_u32_b32 v1, s19, v1
	v_cmp_eq_u32_e32 vcc, 0, v1
	s_and_saveexec_b64 s[20:21], vcc
	s_cbranch_execz .LBB0_691
	s_bcnt1_i32_b64 s2, s[18:19]
	v_mov_b32_e32 v2, 0x3000
	v_mov_b32_e32 v3, s2
	global_atomic_add v2, v2, v3, s[90:91] offset:1024 sc0

; __device__ __forceinline__ unsigned xb_ld(unsigned* p)              { return __hip_atomic_load(p, __ATOMIC_RELAXED, __HIP_MEMORY_SCOPE_AGENT); }
; __device__ __forceinline__ unsigned xb_add(unsigned* p, unsigned v) { return __hip_atomic_fetch_add(p, v, __ATOMIC_RELAXED, __HIP_MEMORY_SCOPE_AGENT); }
; #define XB_SPIN(cond, bar) do { unsigned _sp = 0; while (cond) { __builtin_amdgcn_s_sleep(1); \
;     if ((++_sp & 255u) == 0u) { if (xb_ld(&(bar)[XB_TMO])) break; if (_sp > XB_SPIN_CAP) { atomicAdd(&(bar)[XB_TMO], 1u); break; } } } } while (0)
; __device__ __forceinline__ void xcd_barrier(const XcdBarrier& b) {
;     ...
;             if (og + 1u == (tg + 1u) * nx) xb_add(&bar[XB_TOPGEN], 1u);
;             else XB_SPIN(xb_ld(&bar[XB_TOPGEN]) == tg, bar);
;             __builtin_amdgcn_fence(__ATOMIC_ACQUIRE, "agent");
;             xb_add(&bar[XB_XGEN(b.x)], 1u);
.LBB0_705:
	s_or_b64 exec, exec, s[18:19]
	s_mov_b64 s[18:19], exec
	v_mbcnt_lo_u32_b32 v0, s18, 0
	v_mbcnt_hi_u32_b32 v0, s19, v0
	v_cmp_eq_u32_e32 vcc, 0, v0
	s_waitcnt vmcnt(0)
	s_and_saveexec_b64 s[20:21], vcc
	s_cbranch_execz .LBB0_707
	s_bcnt1_i32_b64 s2, s[18:19]
	v_mov_b32_e32 v0, 0x2000
	v_mov_b32_e32 v1, s2
	global_atomic_add v0, v1, s[16:17] offset:1024

; __device__ __forceinline__ unsigned xb_ld(unsigned* p)              { return __hip_atomic_load(p, __ATOMIC_RELAXED, __HIP_MEMORY_SCOPE_AGENT); }
; __device__ __forceinline__ unsigned xb_add(unsigned* p, unsigned v) { return __hip_atomic_fetch_add(p, v, __ATOMIC_RELAXED, __HIP_MEMORY_SCOPE_AGENT); }
; #define XB_SPIN(cond, bar) do { unsigned _sp = 0; while (cond) { __builtin_amdgcn_s_sleep(1); \
;     if ((++_sp & 255u) == 0u) { if (xb_ld(&(bar)[XB_TMO])) break; if (_sp > XB_SPIN_CAP) { atomicAdd(&(bar)[XB_TMO], 1u); break; } } } } while (0)
; __device__ __forceinline__ void xcd_barrier(const XcdBarrier& b) {
;     ...
;         const unsigned old = xb_add(&bar[XB_XSUB(b.x)], 1u);
;         const unsigned gen = old / nloc;
;         if (old + 1u == (gen + 1u) * nloc) {
;             __builtin_amdgcn_fence(__ATOMIC_RELEASE, "agent");
;             asm volatile("s_waitcnt vmcnt(0)" ::: "memory");
;             const unsigned og = xb_add(&bar[XB_TOP], 1u);
;             const unsigned tg = og / nx;
;             if (og + 1u == (tg + 1u) * nx) xb_add(&bar[XB_TOPGEN], 1u);
;             else XB_SPIN(xb_ld(&bar[XB_TOPGEN]) == tg, bar);
;             __builtin_amdgcn_fence(__ATOMIC_ACQUIRE, "agent");
;             xb_add(&bar[XB_XGEN(b.x)], 1u);
;             asm volatile("s_waitcnt vmcnt(0)" ::: "memory");
;         } else {
;             XB_SPIN(xb_ld(&bar[XB_XGEN(b.x)]) == gen, bar);
;             __builtin_amdgcn_fence(__ATOMIC_ACQUIRE, "agent");
;             asm volatile("s_waitcnt vmcnt(0)" ::: "memory");
.LBB0_1160:
	s_or_b64 exec, exec, s[18:19]
	v_cvt_f32_u32_e32 v4, v2
	s_waitcnt vmcnt(0)
	v_readfirstlane_b32 s2, v3
	v_sub_u32_e32 v3, 0, v2
	v_rcp_iflag_f32_e32 v4, v4
	v_add_u32_e32 v5, s2, v1
	v_mul_f32_e32 v4, 0x4f7ffffe, v4
	v_cvt_u32_f32_e32 v4, v4
	v_mul_lo_u32 v1, v3, v4
	v_mul_hi_u32 v1, v4, v1
	v_add_u32_e32 v1, v4, v1
	v_mul_hi_u32 v1, v5, v1
	v_mul_lo_u32 v3, v1, v2
	v_sub_u32_e32 v3, v5, v3
	v_add_u32_e32 v4, 1, v1
	v_cmp_ge_u32_e32 vcc, v3, v2
	s_nop 1
	v_cndmask_b32_e32 v1, v1, v4, vcc
	v_sub_u32_e32 v4, v3, v2
	v_cndmask_b32_e32 v3, v3, v4, vcc
	v_add_u32_e32 v4, 1, v1
	v_cmp_ge_u32_e32 vcc, v3, v2
	v_add_u32_e32 v3, 1, v5
	s_nop 0
	v_cndmask_b32_e32 v1, v1, v4, vcc
	v_mul_lo_u32 v4, v2, v1
	v_add_u32_e32 v2, v4, v2
	v_cmp_ne_u32_e32 vcc, v3, v2
	s_and_saveexec_b64 s[12:13], vcc
	s_xor_b64 s[16:17], exec, s[12:13]
	s_cbranch_execz .LBB0_1174
	buffer_inv sc1
	s_waitcnt lgkmcnt(0)
	v_mov_b32_e32 v0, 0x2000
	global_load_dword v0, v0, s[8:9] offset:1024 sc1
	s_add_u32 s20, s8, 0x2400
	s_addc_u32 s21, s9, 0
	s_waitcnt vmcnt(0)
	v_cmp_eq_u32_e32 vcc, v0, v1
	s_and_saveexec_b64 s[18:19], vcc
	s_cbranch_execz .LBB0_1173
	s_mov_b32 s2, 1
	s_mov_b64 s[22:23], 0
	v_mov_b32_e32 v0, 0
	s_branch .LBB0_1164

; __device__ __forceinline__ unsigned xb_ld(unsigned* p)              { return __hip_atomic_load(p, __ATOMIC_RELAXED, __HIP_MEMORY_SCOPE_AGENT); }
; __device__ __forceinline__ unsigned xb_add(unsigned* p, unsigned v) { return __hip_atomic_fetch_add(p, v, __ATOMIC_RELAXED, __HIP_MEMORY_SCOPE_AGENT); }
; #define XB_SPIN(cond, bar) do { unsigned _sp = 0; while (cond) { __builtin_amdgcn_s_sleep(1); \
;     if ((++_sp & 255u) == 0u) { if (xb_ld(&(bar)[XB_TMO])) break; if (_sp > XB_SPIN_CAP) { atomicAdd(&(bar)[XB_TMO], 1u); break; } } } } while (0)
; __device__ __forceinline__ void xcd_barrier(const XcdBarrier& b) {
;     ...
;         if (old + 1u == (gen + 1u) * nloc) {
;             __builtin_amdgcn_fence(__ATOMIC_RELEASE, "agent");
;             asm volatile("s_waitcnt vmcnt(0)" ::: "memory");
;             const unsigned og = xb_add(&bar[XB_TOP], 1u);
;             const unsigned tg = og / nx;
;             if (og + 1u == (tg + 1u) * nx) xb_add(&bar[XB_TOPGEN], 1u);
;             else XB_SPIN(xb_ld(&bar[XB_TOPGEN]) == tg, bar);
;             __builtin_amdgcn_fence(__ATOMIC_ACQUIRE, "agent");
;             xb_add(&bar[XB_XGEN(b.x)], 1u);
;             asm volatile("s_waitcnt vmcnt(0)" ::: "memory");
;         } else {
;             XB_SPIN(xb_ld(&bar[XB_XGEN(b.x)]) == gen, bar);
;             __builtin_amdgcn_fence(__ATOMIC_ACQUIRE, "agent");
;             asm volatile("s_waitcnt vmcnt(0)" ::: "memory");
.LBB0_1173:
	s_or_b64 exec, exec, s[18:19]
	s_waitcnt vmcnt(0)
	s_waitcnt vmcnt(0)
.LBB0_1174:
	s_andn2_saveexec_b64 s[12:13], s[16:17]
	s_cbranch_execz .LBB0_1194
	s_mov_b64 s[16:17], exec
	buffer_wbl2 sc1
	buffer_inv sc1
	s_waitcnt lgkmcnt(0)
	s_waitcnt vmcnt(0)
	v_mbcnt_lo_u32_b32 v1, s16, 0
	v_mbcnt_hi_u32_b32 v1, s17, v1
	v_cmp_eq_u32_e32 vcc, 0, v1
	s_and_saveexec_b64 s[18:19], vcc
	s_cbranch_execz .LBB0_1177
	s_bcnt1_i32_b64 s2, s[16:17]
	v_mov_b32_e32 v2, 0x3000
	v_mov_b32_e32 v3, s2
	global_atomic_add v2, v2, v3, s[90:91] offset:1024 sc0

; __device__ __forceinline__ unsigned xb_ld(unsigned* p)              { return __hip_atomic_load(p, __ATOMIC_RELAXED, __HIP_MEMORY_SCOPE_AGENT); }
; __device__ __forceinline__ unsigned xb_add(unsigned* p, unsigned v) { return __hip_atomic_fetch_add(p, v, __ATOMIC_RELAXED, __HIP_MEMORY_SCOPE_AGENT); }
; #define XB_SPIN(cond, bar) do { unsigned _sp = 0; while (cond) { __builtin_amdgcn_s_sleep(1); \
;     if ((++_sp & 255u) == 0u) { if (xb_ld(&(bar)[XB_TMO])) break; if (_sp > XB_SPIN_CAP) { atomicAdd(&(bar)[XB_TMO], 1u); break; } } } } while (0)
; __device__ __forceinline__ void xcd_barrier(const XcdBarrier& b) {
;     ...
;             if (og + 1u == (tg + 1u) * nx) xb_add(&bar[XB_TOPGEN], 1u);
;             else XB_SPIN(xb_ld(&bar[XB_TOPGEN]) == tg, bar);
;             __builtin_amdgcn_fence(__ATOMIC_ACQUIRE, "agent");
;             xb_add(&bar[XB_XGEN(b.x)], 1u);
.LBB0_1191:
	s_or_b64 exec, exec, s[16:17]
	s_mov_b64 s[16:17], exec
	v_mbcnt_lo_u32_b32 v0, s16, 0
	v_mbcnt_hi_u32_b32 v0, s17, v0
	v_cmp_eq_u32_e32 vcc, 0, v0
	s_waitcnt vmcnt(0)
	s_and_saveexec_b64 s[18:19], vcc
	s_cbranch_execz .LBB0_1193
	s_bcnt1_i32_b64 s2, s[16:17]
	v_mov_b32_e32 v0, 0x2000
	v_mov_b32_e32 v1, s2
	global_atomic_add v0, v1, s[8:9] offset:1024

; __device__ __forceinline__ unsigned xb_ld(unsigned* p)              { return __hip_atomic_load(p, __ATOMIC_RELAXED, __HIP_MEMORY_SCOPE_AGENT); }
; __device__ __forceinline__ unsigned xb_add(unsigned* p, unsigned v) { return __hip_atomic_fetch_add(p, v, __ATOMIC_RELAXED, __HIP_MEMORY_SCOPE_AGENT); }
; #define XB_SPIN(cond, bar) do { unsigned _sp = 0; while (cond) { __builtin_amdgcn_s_sleep(1); \
;     if ((++_sp & 255u) == 0u) { if (xb_ld(&(bar)[XB_TMO])) break; if (_sp > XB_SPIN_CAP) { atomicAdd(&(bar)[XB_TMO], 1u); break; } } } } while (0)
; __device__ __forceinline__ void xcd_barrier(const XcdBarrier& b) {
;     ...
;         const unsigned old = xb_add(&bar[XB_XSUB(b.x)], 1u);
;         const unsigned gen = old / nloc;
;         if (old + 1u == (gen + 1u) * nloc) {
;             __builtin_amdgcn_fence(__ATOMIC_RELEASE, "agent");
;             asm volatile("s_waitcnt vmcnt(0)" ::: "memory");
;             const unsigned og = xb_add(&bar[XB_TOP], 1u);
;             const unsigned tg = og / nx;
;             if (og + 1u == (tg + 1u) * nx) xb_add(&bar[XB_TOPGEN], 1u);
;             else XB_SPIN(xb_ld(&bar[XB_TOPGEN]) == tg, bar);
;             __builtin_amdgcn_fence(__ATOMIC_ACQUIRE, "agent");
;             xb_add(&bar[XB_XGEN(b.x)], 1u);
;             asm volatile("s_waitcnt vmcnt(0)" ::: "memory");
;         } else {
;             XB_SPIN(xb_ld(&bar[XB_XGEN(b.x)]) == gen, bar);
;             __builtin_amdgcn_fence(__ATOMIC_ACQUIRE, "agent");
;             asm volatile("s_waitcnt vmcnt(0)" ::: "memory");
.LBB0_1365:
	s_or_b64 exec, exec, s[18:19]
	v_cvt_f32_u32_e32 v4, v2
	s_waitcnt vmcnt(0)
	v_readfirstlane_b32 s2, v3
	v_sub_u32_e32 v3, 0, v2
	v_rcp_iflag_f32_e32 v4, v4
	v_add_u32_e32 v5, s2, v1
	v_mul_f32_e32 v4, 0x4f7ffffe, v4
	v_cvt_u32_f32_e32 v4, v4
	v_mul_lo_u32 v1, v3, v4
	v_mul_hi_u32 v1, v4, v1
	v_add_u32_e32 v1, v4, v1
	v_mul_hi_u32 v1, v5, v1
	v_mul_lo_u32 v3, v1, v2
	v_sub_u32_e32 v3, v5, v3
	v_add_u32_e32 v4, 1, v1
	v_cmp_ge_u32_e32 vcc, v3, v2
	s_nop 1
	v_cndmask_b32_e32 v1, v1, v4, vcc
	v_sub_u32_e32 v4, v3, v2
	v_cndmask_b32_e32 v3, v3, v4, vcc
	v_add_u32_e32 v4, 1, v1
	v_cmp_ge_u32_e32 vcc, v3, v2
	v_add_u32_e32 v3, 1, v5
	s_nop 0
	v_cndmask_b32_e32 v1, v1, v4, vcc
	v_mul_lo_u32 v4, v2, v1
	v_add_u32_e32 v2, v4, v2
	v_cmp_ne_u32_e32 vcc, v3, v2
	s_and_saveexec_b64 s[14:15], vcc
	s_xor_b64 s[16:17], exec, s[14:15]
	s_cbranch_execz .LBB0_1379
	buffer_inv sc1
	s_waitcnt lgkmcnt(0)
	v_mov_b32_e32 v0, 0x2000
	global_load_dword v0, v0, s[12:13] offset:1024 sc1
	s_add_u32 s20, s12, 0x2400
	s_addc_u32 s21, s13, 0
	s_waitcnt vmcnt(0)
	v_cmp_eq_u32_e32 vcc, v0, v1
	s_and_saveexec_b64 s[18:19], vcc
	s_cbranch_execz .LBB0_1378
	s_mov_b32 s2, 1
	s_mov_b64 s[22:23], 0
	v_mov_b32_e32 v0, 0
	s_branch .LBB0_1369

; __device__ __forceinline__ unsigned xb_add(unsigned* p, unsigned v) { return __hip_atomic_fetch_add(p, v, __ATOMIC_RELAXED, __HIP_MEMORY_SCOPE_AGENT); }
; __device__ __forceinline__ void xcd_barrier(const XcdBarrier& b) {
;     ...
;         if (old + 1u == (gen + 1u) * nloc) {
;             __builtin_amdgcn_fence(__ATOMIC_RELEASE, "agent");
;             asm volatile("s_waitcnt vmcnt(0)" ::: "memory");
;             const unsigned og = xb_add(&bar[XB_TOP], 1u);
.LBB0_1379:
	s_andn2_saveexec_b64 s[14:15], s[16:17]
	s_cbranch_execz .LBB0_1399
	s_mov_b64 s[16:17], exec
	buffer_wbl2 sc1
	buffer_inv sc1
	s_waitcnt lgkmcnt(0)
	s_waitcnt vmcnt(0)
	v_mbcnt_lo_u32_b32 v1, s16, 0
	v_mbcnt_hi_u32_b32 v1, s17, v1
	v_cmp_eq_u32_e32 vcc, 0, v1
	s_and_saveexec_b64 s[18:19], vcc
	s_cbranch_execz .LBB0_1382
	s_bcnt1_i32_b64 s2, s[16:17]
	v_mov_b32_e32 v2, 0x3000
	v_mov_b32_e32 v3, s2
	global_atomic_add v2, v2, v3, s[90:91] offset:1024 sc0

; __device__ __forceinline__ unsigned xb_ld(unsigned* p)              { return __hip_atomic_load(p, __ATOMIC_RELAXED, __HIP_MEMORY_SCOPE_AGENT); }
; __device__ __forceinline__ unsigned xb_add(unsigned* p, unsigned v) { return __hip_atomic_fetch_add(p, v, __ATOMIC_RELAXED, __HIP_MEMORY_SCOPE_AGENT); }
; #define XB_SPIN(cond, bar) do { unsigned _sp = 0; while (cond) { __builtin_amdgcn_s_sleep(1); \
;     if ((++_sp & 255u) == 0u) { if (xb_ld(&(bar)[XB_TMO])) break; if (_sp > XB_SPIN_CAP) { atomicAdd(&(bar)[XB_TMO], 1u); break; } } } } while (0)
; __device__ __forceinline__ void xcd_barrier(const XcdBarrier& b) {
;     ...
;             if (og + 1u == (tg + 1u) * nx) xb_add(&bar[XB_TOPGEN], 1u);
;             else XB_SPIN(xb_ld(&bar[XB_TOPGEN]) == tg, bar);
;             __builtin_amdgcn_fence(__ATOMIC_ACQUIRE, "agent");
;             xb_add(&bar[XB_XGEN(b.x)], 1u);
.LBB0_1396:
	s_or_b64 exec, exec, s[16:17]
	s_mov_b64 s[16:17], exec
	v_mbcnt_lo_u32_b32 v0, s16, 0
	v_mbcnt_hi_u32_b32 v0, s17, v0
	v_cmp_eq_u32_e32 vcc, 0, v0
	s_waitcnt vmcnt(0)
	s_and_saveexec_b64 s[18:19], vcc
	s_cbranch_execz .LBB0_1398
	s_bcnt1_i32_b64 s2, s[16:17]
	v_mov_b32_e32 v0, 0x2000
	v_mov_b32_e32 v1, s2
	global_atomic_add v0, v1, s[12:13] offset:1024

; __device__ __forceinline__ unsigned xb_ld(unsigned* p)              { return __hip_atomic_load(p, __ATOMIC_RELAXED, __HIP_MEMORY_SCOPE_AGENT); }
; __device__ __forceinline__ unsigned xb_add(unsigned* p, unsigned v) { return __hip_atomic_fetch_add(p, v, __ATOMIC_RELAXED, __HIP_MEMORY_SCOPE_AGENT); }
; #define XB_SPIN(cond, bar) do { unsigned _sp = 0; while (cond) { __builtin_amdgcn_s_sleep(1); \
;     if ((++_sp & 255u) == 0u) { if (xb_ld(&(bar)[XB_TMO])) break; if (_sp > XB_SPIN_CAP) { atomicAdd(&(bar)[XB_TMO], 1u); break; } } } } while (0)
; __device__ __forceinline__ void xcd_barrier(const XcdBarrier& b) {
;     ...
;         const unsigned old = xb_add(&bar[XB_XSUB(b.x)], 1u);
;         const unsigned gen = old / nloc;
;         if (old + 1u == (gen + 1u) * nloc) {
;             __builtin_amdgcn_fence(__ATOMIC_RELEASE, "agent");
;             asm volatile("s_waitcnt vmcnt(0)" ::: "memory");
;             const unsigned og = xb_add(&bar[XB_TOP], 1u);
;             const unsigned tg = og / nx;
;             if (og + 1u == (tg + 1u) * nx) xb_add(&bar[XB_TOPGEN], 1u);
;             else XB_SPIN(xb_ld(&bar[XB_TOPGEN]) == tg, bar);
;             __builtin_amdgcn_fence(__ATOMIC_ACQUIRE, "agent");
;             xb_add(&bar[XB_XGEN(b.x)], 1u);
;             asm volatile("s_waitcnt vmcnt(0)" ::: "memory");
;         } else {
;             XB_SPIN(xb_ld(&bar[XB_XGEN(b.x)]) == gen, bar);
;             __builtin_amdgcn_fence(__ATOMIC_ACQUIRE, "agent");
;             asm volatile("s_waitcnt vmcnt(0)" ::: "memory");
.LBB0_1517:
	s_or_b64 exec, exec, s[18:19]
	v_cvt_f32_u32_e32 v4, v2
	s_waitcnt vmcnt(0)
	v_readfirstlane_b32 s2, v3
	s_add_u32 s12, s12, 0x2400
	s_addc_u32 s13, s13, 0
	v_rcp_iflag_f32_e32 v4, v4
	v_add_u32_e32 v5, s2, v1
	v_mul_f32_e32 v3, 0x4f7ffffe, v4
	v_cvt_u32_f32_e32 v3, v3
	v_sub_u32_e32 v4, 0, v2
	v_mul_lo_u32 v1, v4, v3
	v_mul_hi_u32 v1, v3, v1
	v_add_u32_e32 v1, v3, v1
	v_mul_hi_u32 v1, v5, v1
	v_mul_lo_u32 v3, v1, v2
	v_sub_u32_e32 v3, v5, v3
	v_add_u32_e32 v4, 1, v1
	v_cmp_ge_u32_e32 vcc, v3, v2
	s_nop 1
	v_cndmask_b32_e32 v1, v1, v4, vcc
	v_sub_u32_e32 v4, v3, v2
	v_cndmask_b32_e32 v3, v3, v4, vcc
	v_add_u32_e32 v4, 1, v1
	v_cmp_ge_u32_e32 vcc, v3, v2
	v_add_u32_e32 v3, 1, v5
	s_nop 0
	v_cndmask_b32_e32 v1, v1, v4, vcc
	v_mul_lo_u32 v4, v2, v1
	v_add_u32_e32 v2, v4, v2
	v_cmp_ne_u32_e32 vcc, v3, v2
	s_and_saveexec_b64 s[10:11], vcc
	s_xor_b64 s[16:17], exec, s[10:11]
	s_cbranch_execz .LBB0_1531
	buffer_inv sc1
	s_waitcnt lgkmcnt(0)
	v_mov_b32_e32 v0, 0
	global_load_dword v2, v0, s[12:13] sc1
	s_waitcnt vmcnt(0)
	v_cmp_eq_u32_e32 vcc, v2, v1
	s_and_saveexec_b64 s[18:19], vcc
	s_cbranch_execz .LBB0_1530
	s_mov_b32 s2, 1
	s_mov_b64 s[20:21], 0
	s_branch .LBB0_1521

; __device__ __forceinline__ unsigned xb_add(unsigned* p, unsigned v) { return __hip_atomic_fetch_add(p, v, __ATOMIC_RELAXED, __HIP_MEMORY_SCOPE_AGENT); }
; __device__ __forceinline__ void xcd_barrier(const XcdBarrier& b) {
;     ...
;         if (old + 1u == (gen + 1u) * nloc) {
;             __builtin_amdgcn_fence(__ATOMIC_RELEASE, "agent");
;             asm volatile("s_waitcnt vmcnt(0)" ::: "memory");
;             const unsigned og = xb_add(&bar[XB_TOP], 1u);
.LBB0_1531:
	s_andn2_saveexec_b64 s[10:11], s[16:17]
	s_cbranch_execz .LBB0_1551
	s_mov_b64 s[16:17], exec
	buffer_wbl2 sc1
	buffer_inv sc1
	s_waitcnt lgkmcnt(0)
	s_waitcnt vmcnt(0)
	v_mbcnt_lo_u32_b32 v1, s16, 0
	v_mbcnt_hi_u32_b32 v1, s17, v1
	v_cmp_eq_u32_e32 vcc, 0, v1
	s_and_saveexec_b64 s[18:19], vcc
	s_cbranch_execz .LBB0_1534
	s_bcnt1_i32_b64 s2, s[16:17]
	v_mov_b32_e32 v2, 0x3000
	v_mov_b32_e32 v3, s2
	global_atomic_add v2, v2, v3, s[90:91] offset:1024 sc0

; __device__ __forceinline__ unsigned xb_ld(unsigned* p)              { return __hip_atomic_load(p, __ATOMIC_RELAXED, __HIP_MEMORY_SCOPE_AGENT); }
; __device__ __forceinline__ unsigned xb_add(unsigned* p, unsigned v) { return __hip_atomic_fetch_add(p, v, __ATOMIC_RELAXED, __HIP_MEMORY_SCOPE_AGENT); }
; #define XB_SPIN(cond, bar) do { unsigned _sp = 0; while (cond) { __builtin_amdgcn_s_sleep(1); \
;     if ((++_sp & 255u) == 0u) { if (xb_ld(&(bar)[XB_TMO])) break; if (_sp > XB_SPIN_CAP) { atomicAdd(&(bar)[XB_TMO], 1u); break; } } } } while (0)
; __device__ __forceinline__ void xcd_barrier(const XcdBarrier& b) {
;     asm volatile("s_waitcnt vmcnt(0)" ::: "memory");
;     __syncthreads();
;     if (threadIdx.x == 0) {
;         unsigned* bar = b.bar;
;         __builtin_amdgcn_s_waitcnt(0);
;         unsigned nloc = b.st[0], nx = b.st[1];
;         if (nloc == 0u) { xcd_barrier_complete(bar, b.x, nloc, nx); b.st[0] = nloc; b.st[1] = nx; }
;         const unsigned old = xb_add(&bar[XB_XSUB(b.x)], 1u);
;         const unsigned gen = old / nloc;
;         if (old + 1u == (gen + 1u) * nloc) {
;             __builtin_amdgcn_fence(__ATOMIC_RELEASE, "agent");
;             asm volatile("s_waitcnt vmcnt(0)" ::: "memory");
;             const unsigned og = xb_add(&bar[XB_TOP], 1u);
;             const unsigned tg = og / nx;
;             if (og + 1u == (tg + 1u) * nx) xb_add(&bar[XB_TOPGEN], 1u);
;             else XB_SPIN(xb_ld(&bar[XB_TOPGEN]) == tg, bar);
;             __builtin_amdgcn_fence(__ATOMIC_ACQUIRE, "agent");
;             xb_add(&bar[XB_XGEN(b.x)], 1u);
;             asm volatile("s_waitcnt vmcnt(0)" ::: "memory");
;         } else {
;             XB_SPIN(xb_ld(&bar[XB_XGEN(b.x)]) == gen, bar);
;             __builtin_amdgcn_fence(__ATOMIC_ACQUIRE, "agent");
;             asm volatile("s_waitcnt vmcnt(0)" ::: "memory");
;         }
;     }
;     __syncthreads();
; }
.LBB0_1548:
	s_or_b64 exec, exec, s[6:7]
	s_mov_b64 s[6:7], exec
	v_mbcnt_lo_u32_b32 v0, s6, 0
	v_mbcnt_hi_u32_b32 v0, s7, v0
	v_cmp_eq_u32_e32 vcc, 0, v0
	s_waitcnt vmcnt(0)
	s_and_saveexec_b64 s[16:17], vcc
	s_cbranch_execz .LBB0_1550
	s_bcnt1_i32_b64 s2, s[6:7]
	v_mov_b32_e32 v0, 0
	v_mov_b32_e32 v1, s2
	global_atomic_add v0, v1, s[12:13]
